# gla_finish: gate-projection coefficient loads issued back to back after loading the two kernarg pointers once (was 17 pointer reload + wait chains per direction), on top of the epilogue edit
# baseline (speedup 1.0000x reference)
; DI int oidx(int i) { asm volatile("" : "+s"(i)); return i; }
; DI float logsigf_(float x) { return fminf(x, 0.f) - __logf(1.f + __expf(-fabsf(x))); }
; DN void gla_finish_item(const Params& p, int l, int b, int cs, int hh, char* smem) {
;     ...
;     {
;       float a2c[16];
; #pragma unroll
;       for (int q = 0; q < 16; ++q) a2c[q] = p.in[oidx(24)][((size_t)(l * 2 + dir) * 16 + q) * 128 + hh * 32 + dl];
;       const float abv = p.in[oidx(25)][(l * 2 + dir) * 128 + hh * 32 + dl];
;       float lgv[8];
; #pragma unroll
;       for (int li = 0; li < 8; ++li) {
;         int lt = lgrp * 8 + li;
;         float x = abv;
; #pragma unroll
;         for (int q = 0; q < 16; ++q) x += gg[lt * 16 + q] * a2c[q];
;         lgv[li] = logsigf_(x) * (1.f / 16.f);
;       }
.LBB0_1020:
	s_or_b64 exec, exec, s[76:77]
	s_xor_b64 s[82:83], s[80:81], -1
	s_load_dwordx2 s[76:77], s[0:1], 0xc0
	s_load_dwordx2 s[98:99], s[0:1], 0xc8
	v_lshl_or_b32 v152, s84, 11, v75
	v_lshlrev_b64 v[24:25], 2, v[152:153]
	v_lshl_or_b32 v152, s84, 7, v76
	s_mov_b32 s84, 0xbfb8aa3b
	s_mov_b32 s86, 0x3f317217
	s_waitcnt lgkmcnt(0)
	v_lshl_add_u64 v[26:27], s[76:77], 0, v[24:25]
	global_load_dword v29, v[26:27], off
	global_load_dword v30, v[26:27], off offset:512
	global_load_dword v31, v[26:27], off offset:1024
	global_load_dword v33, v[26:27], off offset:1536
	global_load_dword v32, v[26:27], off offset:2048
	global_load_dword v34, v[26:27], off offset:2560
	global_load_dword v35, v[26:27], off offset:3072
	global_load_dword v36, v[26:27], off offset:3584
	v_add_co_u32_e32 v24, vcc, 0x1000, v26
	s_nop 1
	v_addc_co_u32_e32 v25, vcc, 0, v27, vcc
	global_load_dword v37, v[24:25], off
	global_load_dword v38, v[24:25], off offset:512
	global_load_dword v39, v[24:25], off offset:1024
	global_load_dword v79, v[24:25], off offset:1536
	global_load_dword v78, v[24:25], off offset:2048
	global_load_dword v80, v[24:25], off offset:2560
	global_load_dword v81, v[24:25], off offset:3072
	global_load_dword v82, v[24:25], off offset:3584
	v_lshl_add_u64 v[24:25], v[152:153], 2, s[98:99]
	global_load_dword v83, v[24:25], off
	s_mov_b32 s85, 0x7f800000
	ds_read_b128 v[24:27], v66 offset:33024
	ds_read_b128 v[84:87], v66 offset:33040
	ds_read_b128 v[88:91], v66 offset:33056
	ds_read_b128 v[92:95], v66 offset:33072
	s_waitcnt vmcnt(0) lgkmcnt(3)
	v_fma_f32 v24, v29, v24, v83
	v_fmac_f32_e32 v24, v30, v25
	v_fmac_f32_e32 v24, v31, v26
	v_fmac_f32_e32 v24, v33, v27
	s_waitcnt lgkmcnt(2)
	v_fmac_f32_e32 v24, v32, v84
	v_fmac_f32_e32 v24, v34, v85
	v_fmac_f32_e32 v24, v35, v86
	v_fmac_f32_e32 v24, v36, v87
	s_waitcnt lgkmcnt(1)
	v_fmac_f32_e32 v24, v37, v88
	v_fmac_f32_e32 v24, v38, v89
	v_fmac_f32_e32 v24, v39, v90
	v_fmac_f32_e32 v24, v79, v91
	s_waitcnt lgkmcnt(0)
	v_fmac_f32_e32 v24, v78, v92
	v_fmac_f32_e32 v24, v80, v93
	v_fmac_f32_e32 v24, v81, v94
	v_fmac_f32_e32 v24, v82, v95
	v_min_f32_e32 v25, 0, v24
	v_mul_f32_e64 v24, |v24|, s84
	v_exp_f32_e32 v24, v24
	s_nop 0
	v_add_f32_e32 v24, 1.0, v24
	v_cmp_gt_f32_e32 vcc, s33, v24
	s_nop 1
	v_cndmask_b32_e64 v26, 0, 32, vcc
	v_ldexp_f32 v24, v24, v26
	v_log_f32_e32 v24, v24
	s_nop 0
	v_mul_f32_e32 v26, 0x3f317217, v24
	v_fma_f32 v26, v24, s86, -v26
	v_fmac_f32_e32 v26, 0x3377d1cf, v24
	v_fmac_f32_e32 v26, 0x3f317217, v24
	v_cmp_lt_f32_e64 s[76:77], |v24|, s85
	s_nop 1
	v_cndmask_b32_e64 v24, v24, v26, s[76:77]
	v_cndmask_b32_e32 v26, 0, v196, vcc
	v_sub_f32_e32 v24, v24, v26
	v_sub_f32_e32 v24, v25, v24
	v_mul_f32_e32 v28, 0x3d800000, v24
	ds_read_b128 v[24:27], v66 offset:33088
	s_waitcnt lgkmcnt(0)
	v_fma_f32 v84, v29, v24, v83
	v_fmac_f32_e32 v84, v30, v25
	v_fmac_f32_e32 v84, v31, v26
	v_fmac_f32_e32 v84, v33, v27
	ds_read_b128 v[24:27], v66 offset:33104
	s_waitcnt lgkmcnt(0)
	v_fmac_f32_e32 v84, v32, v24
	v_fmac_f32_e32 v84, v34, v25
	v_fmac_f32_e32 v84, v35, v26
	v_fmac_f32_e32 v84, v36, v27
	ds_read_b128 v[24:27], v66 offset:33120
	s_waitcnt lgkmcnt(0)
	v_fmac_f32_e32 v84, v37, v24
	v_fmac_f32_e32 v84, v38, v25
	v_fmac_f32_e32 v84, v39, v26
	v_fmac_f32_e32 v84, v79, v27
	ds_read_b128 v[24:27], v66 offset:33136
	s_waitcnt lgkmcnt(0)
	v_fmac_f32_e32 v84, v78, v24
	v_fmac_f32_e32 v84, v80, v25
	v_fmac_f32_e32 v84, v81, v26
	v_fmac_f32_e32 v84, v82, v27
	v_mul_f32_e64 v25, |v84|, s84
	v_exp_f32_e32 v25, v25
	v_min_f32_e32 v24, 0, v84
	v_add_f32_e32 v25, 1.0, v25
	v_cmp_gt_f32_e32 vcc, s33, v25
	s_nop 1
	v_cndmask_b32_e64 v26, 0, 32, vcc
	v_ldexp_f32 v25, v25, v26
	v_log_f32_e32 v25, v25
	s_nop 0
	v_mul_f32_e32 v26, 0x3f317217, v25
	v_fma_f32 v26, v25, s86, -v26
	v_fmac_f32_e32 v26, 0x3377d1cf, v25
	v_fmac_f32_e32 v26, 0x3f317217, v25
	v_cmp_lt_f32_e64 s[76:77], |v25|, s85
	s_nop 1
	v_cndmask_b32_e64 v25, v25, v26, s[76:77]
	v_cndmask_b32_e32 v26, 0, v196, vcc
	v_sub_f32_e32 v25, v25, v26
	v_sub_f32_e32 v24, v24, v25
	v_mul_f32_e32 v84, 0x3d800000, v24
	ds_read_b128 v[24:27], v66 offset:33152
	s_waitcnt lgkmcnt(0)
	v_fma_f32 v85, v29, v24, v83
	v_fmac_f32_e32 v85, v30, v25
	v_fmac_f32_e32 v85, v31, v26
	v_fmac_f32_e32 v85, v33, v27
	ds_read_b128 v[24:27], v66 offset:33168
	s_waitcnt lgkmcnt(0)
	v_fmac_f32_e32 v85, v32, v24
	v_fmac_f32_e32 v85, v34, v25
	v_fmac_f32_e32 v85, v35, v26
	v_fmac_f32_e32 v85, v36, v27
	ds_read_b128 v[24:27], v66 offset:33184
	s_waitcnt lgkmcnt(0)
	v_fmac_f32_e32 v85, v37, v24
	v_fmac_f32_e32 v85, v38, v25
	v_fmac_f32_e32 v85, v39, v26
	v_fmac_f32_e32 v85, v79, v27
	ds_read_b128 v[24:27], v66 offset:33200
	s_waitcnt lgkmcnt(0)
	v_fmac_f32_e32 v85, v78, v24
	v_fmac_f32_e32 v85, v80, v25
	v_fmac_f32_e32 v85, v81, v26
	v_fmac_f32_e32 v85, v82, v27
	v_mul_f32_e64 v25, |v85|, s84
	v_exp_f32_e32 v25, v25
	v_min_f32_e32 v24, 0, v85
	v_add_f32_e32 v25, 1.0, v25
	v_cmp_gt_f32_e32 vcc, s33, v25
	s_nop 1
	v_cndmask_b32_e64 v26, 0, 32, vcc
	v_ldexp_f32 v25, v25, v26
	v_log_f32_e32 v25, v25
	s_nop 0
	v_mul_f32_e32 v26, 0x3f317217, v25
	v_fma_f32 v26, v25, s86, -v26
	v_fmac_f32_e32 v26, 0x3377d1cf, v25
	v_fmac_f32_e32 v26, 0x3f317217, v25
	v_cmp_lt_f32_e64 s[76:77], |v25|, s85
	s_nop 1
	v_cndmask_b32_e64 v25, v25, v26, s[76:77]
	v_cndmask_b32_e32 v26, 0, v196, vcc
	v_sub_f32_e32 v25, v25, v26
	v_sub_f32_e32 v24, v24, v25
	v_mul_f32_e32 v85, 0x3d800000, v24
	ds_read_b128 v[24:27], v66 offset:33216
	s_waitcnt lgkmcnt(0)
	v_fma_f32 v86, v29, v24, v83
	v_fmac_f32_e32 v86, v30, v25
	v_fmac_f32_e32 v86, v31, v26
	v_fmac_f32_e32 v86, v33, v27
	ds_read_b128 v[24:27], v66 offset:33232
	s_waitcnt lgkmcnt(0)
; DI float logsigf_(float x) { return fminf(x, 0.f) - __logf(1.f + __expf(-fabsf(x))); }
; DN void gla_finish_item(const Params& p, int l, int b, int cs, int hh, char* smem) {
;     ...
;       float lgv[8];
; #pragma unroll
;       for (int li = 0; li < 8; ++li) {
;         int lt = lgrp * 8 + li;
;         float x = abv;
; #pragma unroll
;         for (int q = 0; q < 16; ++q) x += gg[lt * 16 + q] * a2c[q];
;         lgv[li] = logsigf_(x) * (1.f / 16.f);
;       }
;       if (dir == 0) {
; #pragma unroll
;         for (int li = 1; li < 8; ++li) lgv[li] += lgv[li - 1];
;         segs[lgrp * 32 + dl] = lgv[7];
;       } else {
; #pragma unroll
;     ...
;         segs[lgrp * 32 + dl] = lgv[0];
;       }
	v_fmac_f32_e32 v86, v32, v24
	v_fmac_f32_e32 v86, v34, v25
	v_fmac_f32_e32 v86, v35, v26
	v_fmac_f32_e32 v86, v36, v27
	ds_read_b128 v[24:27], v66 offset:33248
	s_waitcnt lgkmcnt(0)
	v_fmac_f32_e32 v86, v37, v24
	v_fmac_f32_e32 v86, v38, v25
	v_fmac_f32_e32 v86, v39, v26
	v_fmac_f32_e32 v86, v79, v27
	ds_read_b128 v[24:27], v66 offset:33264
	s_waitcnt lgkmcnt(0)
	v_fmac_f32_e32 v86, v78, v24
	v_fmac_f32_e32 v86, v80, v25
	v_fmac_f32_e32 v86, v81, v26
	v_fmac_f32_e32 v86, v82, v27
	v_mul_f32_e64 v25, |v86|, s84
	v_exp_f32_e32 v25, v25
	v_min_f32_e32 v24, 0, v86
	ds_read_b128 v[86:89], v66 offset:33280
	v_add_f32_e32 v25, 1.0, v25
	v_cmp_gt_f32_e32 vcc, s33, v25
	s_nop 1
	v_cndmask_b32_e64 v26, 0, 32, vcc
	v_ldexp_f32 v25, v25, v26
	v_log_f32_e32 v25, v25
	s_nop 0
	v_mul_f32_e32 v26, 0x3f317217, v25
	v_fma_f32 v26, v25, s86, -v26
	v_fmac_f32_e32 v26, 0x3377d1cf, v25
	v_fmac_f32_e32 v26, 0x3f317217, v25
	v_cmp_lt_f32_e64 s[76:77], |v25|, s85
	s_nop 1
	v_cndmask_b32_e64 v25, v25, v26, s[76:77]
	v_cndmask_b32_e32 v26, 0, v196, vcc
	v_sub_f32_e32 v25, v25, v26
	v_sub_f32_e32 v24, v24, v25
	s_waitcnt lgkmcnt(0)
	v_fma_f32 v25, v29, v86, v83
	v_fmac_f32_e32 v25, v30, v87
	v_fmac_f32_e32 v25, v31, v88
	v_fmac_f32_e32 v25, v33, v89
	ds_read_b128 v[86:89], v66 offset:33296
	v_mul_f32_e32 v24, 0x3d800000, v24
	s_waitcnt lgkmcnt(0)
	v_fmac_f32_e32 v25, v32, v86
	v_fmac_f32_e32 v25, v34, v87
	v_fmac_f32_e32 v25, v35, v88
	v_fmac_f32_e32 v25, v36, v89
	ds_read_b128 v[86:89], v66 offset:33312
	s_waitcnt lgkmcnt(0)
	v_fmac_f32_e32 v25, v37, v86
	v_fmac_f32_e32 v25, v38, v87
	v_fmac_f32_e32 v25, v39, v88
	v_fmac_f32_e32 v25, v79, v89
	ds_read_b128 v[86:89], v66 offset:33328
	s_waitcnt lgkmcnt(0)
	v_fmac_f32_e32 v25, v78, v86
	v_fmac_f32_e32 v25, v80, v87
	v_fmac_f32_e32 v25, v81, v88
	v_fmac_f32_e32 v25, v82, v89
	v_min_f32_e32 v26, 0, v25
	v_mul_f32_e64 v25, |v25|, s84
	v_exp_f32_e32 v25, v25
	ds_read_b128 v[86:89], v66 offset:33344
	v_add_f32_e32 v25, 1.0, v25
	v_cmp_gt_f32_e32 vcc, s33, v25
	s_nop 1
	v_cndmask_b32_e64 v27, 0, 32, vcc
	v_ldexp_f32 v25, v25, v27
	v_log_f32_e32 v25, v25
	s_nop 0
	v_mul_f32_e32 v27, 0x3f317217, v25
	v_fma_f32 v27, v25, s86, -v27
	v_fmac_f32_e32 v27, 0x3377d1cf, v25
	v_fmac_f32_e32 v27, 0x3f317217, v25
	v_cmp_lt_f32_e64 s[76:77], |v25|, s85
	s_nop 1
	v_cndmask_b32_e64 v25, v25, v27, s[76:77]
	v_cndmask_b32_e32 v27, 0, v196, vcc
	v_sub_f32_e32 v25, v25, v27
	v_sub_f32_e32 v25, v26, v25
	s_waitcnt lgkmcnt(0)
	v_fma_f32 v26, v29, v86, v83
	v_fmac_f32_e32 v26, v30, v87
	v_fmac_f32_e32 v26, v31, v88
	v_fmac_f32_e32 v26, v33, v89
	ds_read_b128 v[86:89], v66 offset:33360
	v_mul_f32_e32 v25, 0x3d800000, v25
	s_waitcnt lgkmcnt(0)
	v_fmac_f32_e32 v26, v32, v86
	v_fmac_f32_e32 v26, v34, v87
	v_fmac_f32_e32 v26, v35, v88
	v_fmac_f32_e32 v26, v36, v89
	ds_read_b128 v[86:89], v66 offset:33376
	s_waitcnt lgkmcnt(0)
	v_fmac_f32_e32 v26, v37, v86
	v_fmac_f32_e32 v26, v38, v87
	v_fmac_f32_e32 v26, v39, v88
	v_fmac_f32_e32 v26, v79, v89
	ds_read_b128 v[86:89], v66 offset:33392
	s_waitcnt lgkmcnt(0)
	v_fmac_f32_e32 v26, v78, v86
	v_fmac_f32_e32 v26, v80, v87
	v_fmac_f32_e32 v26, v81, v88
	v_fmac_f32_e32 v26, v82, v89
	v_min_f32_e32 v27, 0, v26
	v_mul_f32_e64 v26, |v26|, s84
	v_exp_f32_e32 v26, v26
	ds_read_b128 v[88:91], v66 offset:33408
	v_add_f32_e32 v26, 1.0, v26
	v_cmp_gt_f32_e32 vcc, s33, v26
	s_nop 1
	v_cndmask_b32_e64 v86, 0, 32, vcc
	v_ldexp_f32 v26, v26, v86
	v_log_f32_e32 v26, v26
	s_nop 0
	v_mul_f32_e32 v86, 0x3f317217, v26
	v_fma_f32 v86, v26, s86, -v86
	v_fmac_f32_e32 v86, 0x3377d1cf, v26
	v_fmac_f32_e32 v86, 0x3f317217, v26
	v_cmp_lt_f32_e64 s[76:77], |v26|, s85
	s_nop 1
	v_cndmask_b32_e64 v26, v26, v86, s[76:77]
	v_cndmask_b32_e32 v86, 0, v196, vcc
	v_sub_f32_e32 v26, v26, v86
	v_sub_f32_e32 v26, v27, v26
	v_mul_f32_e32 v86, 0x3d800000, v26
	s_waitcnt lgkmcnt(0)
	v_fma_f32 v26, v29, v88, v83
	v_fmac_f32_e32 v26, v30, v89
	v_fmac_f32_e32 v26, v31, v90
	v_fmac_f32_e32 v26, v33, v91
	ds_read_b128 v[88:91], v66 offset:33424
	s_waitcnt lgkmcnt(0)
	v_fmac_f32_e32 v26, v32, v88
	v_fmac_f32_e32 v26, v34, v89
	v_fmac_f32_e32 v26, v35, v90
	v_fmac_f32_e32 v26, v36, v91
	ds_read_b128 v[88:91], v66 offset:33440
	s_waitcnt lgkmcnt(0)
	v_fmac_f32_e32 v26, v37, v88
	v_fmac_f32_e32 v26, v38, v89
	v_fmac_f32_e32 v26, v39, v90
	v_fmac_f32_e32 v26, v79, v91
	ds_read_b128 v[88:91], v66 offset:33456
	s_waitcnt lgkmcnt(0)
	v_fmac_f32_e32 v26, v78, v88
	v_fmac_f32_e32 v26, v80, v89
	v_fmac_f32_e32 v26, v81, v90
	v_fmac_f32_e32 v26, v82, v91
	ds_read_b128 v[88:91], v66 offset:33472
	v_min_f32_e32 v27, 0, v26
	v_mul_f32_e64 v26, |v26|, s84
	v_exp_f32_e32 v26, v26
	s_waitcnt lgkmcnt(0)
	v_fmac_f32_e32 v83, v29, v88
	v_fmac_f32_e32 v83, v30, v89
	v_fmac_f32_e32 v83, v31, v90
	v_fmac_f32_e32 v83, v33, v91
	ds_read_b128 v[88:91], v66 offset:33488
	v_add_f32_e32 v26, 1.0, v26
	v_cmp_gt_f32_e32 vcc, s33, v26
	s_waitcnt lgkmcnt(0)
	v_fmac_f32_e32 v83, v32, v88
	ds_read_b128 v[30:33], v66 offset:33504
	v_fmac_f32_e32 v83, v34, v89
	v_fmac_f32_e32 v83, v35, v90
	v_fmac_f32_e32 v83, v36, v91
	v_cndmask_b32_e64 v87, 0, 32, vcc
	s_waitcnt lgkmcnt(0)
	v_fmac_f32_e32 v83, v37, v30
	v_ldexp_f32 v26, v26, v87
	v_fmac_f32_e32 v83, v38, v31
	v_log_f32_e32 v26, v26
	v_fmac_f32_e32 v83, v39, v32
	v_fmac_f32_e32 v83, v79, v33
	ds_read_b128 v[30:33], v66 offset:33520
	v_mul_f32_e32 v87, 0x3f317217, v26
	v_fma_f32 v87, v26, s86, -v87
	v_fmac_f32_e32 v87, 0x3377d1cf, v26
	v_fmac_f32_e32 v87, 0x3f317217, v26
	s_waitcnt lgkmcnt(0)
	v_fmac_f32_e32 v83, v78, v30
	v_cmp_lt_f32_e64 s[76:77], |v26|, s85
	v_fmac_f32_e32 v83, v80, v31
	v_fmac_f32_e32 v83, v81, v32
	v_cndmask_b32_e64 v26, v26, v87, s[76:77]
	v_cndmask_b32_e32 v87, 0, v196, vcc
	v_sub_f32_e32 v26, v26, v87
	v_fmac_f32_e32 v83, v82, v33
	v_sub_f32_e32 v26, v27, v26
	v_mul_f32_e64 v27, |v83|, s84
	v_exp_f32_e32 v27, v27
	v_mul_f32_e32 v87, 0x3d800000, v26
	v_min_f32_e32 v26, 0, v83
	v_add_f32_e32 v27, 1.0, v27
	v_cmp_gt_f32_e32 vcc, s33, v27
	s_nop 1
	v_cndmask_b32_e64 v29, 0, 32, vcc
	v_ldexp_f32 v27, v27, v29
	v_log_f32_e32 v27, v27
	s_nop 0
	v_mul_f32_e32 v29, 0x3f317217, v27
	v_fma_f32 v29, v27, s86, -v29
	v_fmac_f32_e32 v29, 0x3377d1cf, v27
	v_fmac_f32_e32 v29, 0x3f317217, v27
	v_cmp_lt_f32_e64 s[76:77], |v27|, s85
	s_mov_b64 s[84:85], -1
	s_nop 0
	v_cndmask_b32_e64 v27, v27, v29, s[76:77]
	v_cndmask_b32_e32 v29, 0, v196, vcc
	v_sub_f32_e32 v27, v27, v29
	v_sub_f32_e32 v26, v26, v27
	v_cndmask_b32_e64 v27, 0, 1, s[82:83]
	v_mul_f32_e32 v26, 0x3d800000, v26
	v_cmp_ne_u32_e64 s[76:77], 1, v27
	s_andn2_b64 vcc, exec, s[82:83]
	s_cbranch_vccnz .LBB0_1022
	v_add_f32_e32 v27, v87, v26
	v_add_f32_e32 v29, v86, v27
	v_add_f32_e32 v30, v25, v29
	v_add_f32_e32 v31, v24, v30
	v_add_f32_e32 v32, v85, v31
	v_add_f32_e32 v33, v84, v32
	v_add_f32_e32 v34, v28, v33
	s_mov_b64 s[84:85], 0
